# non-temporal stores for the FFN-in activation output (streamed, next read a phase later) so it does not displace the GEMM operand panels in L2
# baseline (speedup 1.0000x reference)
.LBB0_107:
	v_fmamk_f32 v0, v187, 0x3a800000, v154
	v_mul_f32_e32 v34, 0x4b800000, v0
	v_cmp_gt_f32_e32 vcc, s47, v0
	s_lshl_b32 s88, s14, 6
	v_add_u32_e32 v36, 32, v186
	v_cndmask_b32_e32 v0, v0, v34, vcc
	v_rsq_f32_e32 v0, v0
	s_movk_i32 s14, 0x1600
	v_add_u32_e32 v37, 64, v186
	v_mul_f32_e32 v34, 0x45800000, v0
	v_cndmask_b32_e32 v0, v0, v34, vcc
	s_waitcnt vmcnt(0)
	v_pk_fma_f32 v[18:19], v[18:19], v[0:1], v[122:123] op_sel_hi:[1,0,1]
	v_pk_fma_f32 v[20:21], v[20:21], v[0:1], v[124:125] op_sel_hi:[1,0,1]
	v_mul_f32_e32 v34, 0xbfb8aa3b, v18
	v_mul_f32_e32 v35, 0xbfb8aa3b, v19
	v_exp_f32_e32 v34, v34
	v_exp_f32_e32 v35, v35
	v_mul_f32_e32 v38, 0xbfb8aa3b, v20
	v_mul_f32_e32 v39, 0xbfb8aa3b, v21
	v_add_f32_e32 v34, 1.0, v34
	v_add_f32_e32 v35, 1.0, v35
	v_rcp_f32_e32 v34, v34
	v_rcp_f32_e32 v35, v35
	v_exp_f32_e32 v38, v38
	v_exp_f32_e32 v39, v39
	v_pk_fma_f32 v[2:3], v[2:3], v[0:1], v[126:127] op_sel_hi:[1,0,1]
	v_pk_mul_f32 v[18:19], v[18:19], v[34:35]
	v_add_f32_e32 v34, 1.0, v38
	v_add_f32_e32 v35, 1.0, v39
	v_rcp_f32_e32 v34, v34
	v_rcp_f32_e32 v35, v35
	v_pk_mul_f32 v[2:3], v[2:3], v[18:19]
	v_pk_fma_f32 v[4:5], v[4:5], v[0:1], v[128:129] op_sel_hi:[1,0,1]
	v_cvt_pk_f16_f32 v2, v2, v3
	v_pk_mul_f32 v[18:19], v[20:21], v[34:35]
	v_pk_fma_f32 v[6:7], v[6:7], v[0:1], v[114:115] op_sel_hi:[1,0,1]
	v_pk_mul_f32 v[4:5], v[4:5], v[18:19]
	v_pk_fma_f32 v[18:19], v[22:23], v[0:1], v[118:119] op_sel_hi:[1,0,1]
	s_and_b64 vcc, exec, s[2:3]
	v_mul_f32_e32 v3, 0xbfb8aa3b, v18
	v_exp_f32_e32 v20, v3
	v_cvt_pk_f16_f32 v3, v4, v5
	v_mul_f32_e32 v4, 0xbfb8aa3b, v19
	v_exp_f32_e32 v5, v4
	v_add_f32_e32 v4, 1.0, v20
	v_pk_fma_f32 v[20:21], v[24:25], v[0:1], v[120:121] op_sel_hi:[1,0,1]
	v_rcp_f32_e32 v4, v4
	v_add_f32_e32 v5, 1.0, v5
	v_mul_f32_e32 v22, 0xbfb8aa3b, v20
	v_mul_f32_e32 v23, 0xbfb8aa3b, v21
	v_rcp_f32_e32 v5, v5
	v_exp_f32_e32 v22, v22
	v_exp_f32_e32 v23, v23
	v_pk_mul_f32 v[4:5], v[18:19], v[4:5]
	v_add_f32_e32 v18, 1.0, v22
	v_add_f32_e32 v19, 1.0, v23
	v_rcp_f32_e32 v18, v18
	v_rcp_f32_e32 v19, v19
	v_pk_mul_f32 v[4:5], v[6:7], v[4:5]
	v_pk_fma_f32 v[6:7], v[8:9], v[0:1], v[116:117] op_sel_hi:[1,0,1]
	v_cvt_pk_f16_f32 v4, v4, v5
	v_pk_mul_f32 v[8:9], v[20:21], v[18:19]
	v_add_u32_e32 v18, 0x1000, v185
	v_pk_mul_f32 v[6:7], v[6:7], v[8:9]
	s_nop 0
	v_cvt_pk_f16_f32 v5, v6, v7
	v_pk_fma_f32 v[6:7], v[26:27], v[0:1], v[106:107] op_sel_hi:[1,0,1]
	ds_write2_b64 v18, v[2:3], v[4:5] offset0:128 offset1:130
	v_mul_f32_e32 v8, 0xbfb8aa3b, v6
	v_exp_f32_e32 v8, v8
	v_mul_f32_e32 v2, 0xbfb8aa3b, v7
	v_exp_f32_e32 v3, v2
	v_pk_fma_f32 v[4:5], v[10:11], v[0:1], v[110:111] op_sel_hi:[1,0,1]
	v_add_f32_e32 v2, 1.0, v8
	v_pk_fma_f32 v[8:9], v[28:29], v[0:1], v[108:109] op_sel_hi:[1,0,1]
	v_add_f32_e32 v3, 1.0, v3
	v_mul_f32_e32 v10, 0xbfb8aa3b, v8
	v_mul_f32_e32 v11, 0xbfb8aa3b, v9
	v_rcp_f32_e32 v2, v2
	v_rcp_f32_e32 v3, v3
	v_exp_f32_e32 v10, v10
	v_exp_f32_e32 v11, v11
	v_pk_mul_f32 v[2:3], v[6:7], v[2:3]
	v_add_f32_e32 v6, 1.0, v10
	v_add_f32_e32 v7, 1.0, v11
	v_rcp_f32_e32 v6, v6
	v_rcp_f32_e32 v7, v7
	v_pk_mul_f32 v[2:3], v[4:5], v[2:3]
	v_pk_fma_f32 v[4:5], v[12:13], v[0:1], v[112:113] op_sel_hi:[1,0,1]
	v_cvt_pk_f16_f32 v2, v2, v3
	v_pk_mul_f32 v[6:7], v[8:9], v[6:7]
	v_pk_fma_f32 v[10:11], v[32:33], v[0:1], v[104:105] op_sel_hi:[1,0,1]
	v_pk_mul_f32 v[4:5], v[4:5], v[6:7]
	v_pk_fma_f32 v[6:7], v[30:31], v[0:1], v[102:103] op_sel_hi:[1,0,1]
	v_mul_f32_e32 v12, 0xbfb8aa3b, v10
	v_mul_f32_e32 v3, 0xbfb8aa3b, v6
	v_exp_f32_e32 v8, v3
	v_cvt_pk_f16_f32 v3, v4, v5
	v_mul_f32_e32 v4, 0xbfb8aa3b, v7
	v_exp_f32_e32 v5, v4
	v_add_f32_e32 v4, 1.0, v8
	v_mul_f32_e32 v13, 0xbfb8aa3b, v11
	v_rcp_f32_e32 v4, v4
	v_add_f32_e32 v5, 1.0, v5
	v_rcp_f32_e32 v5, v5
	v_exp_f32_e32 v12, v12
	v_exp_f32_e32 v13, v13
	v_pk_fma_f32 v[8:9], v[14:15], v[0:1], v[98:99] op_sel_hi:[1,0,1]
	v_pk_mul_f32 v[4:5], v[6:7], v[4:5]
	v_add_f32_e32 v6, 1.0, v12
	v_add_f32_e32 v7, 1.0, v13
	v_rcp_f32_e32 v6, v6
	v_rcp_f32_e32 v7, v7
	v_pk_mul_f32 v[4:5], v[8:9], v[4:5]
	v_pk_fma_f32 v[8:9], v[16:17], v[0:1], v[100:101] op_sel_hi:[1,0,1]
	v_cvt_pk_f16_f32 v4, v4, v5
	v_pk_mul_f32 v[6:7], v[10:11], v[6:7]
	v_or_b32_e32 v0, v186, v182
	v_pk_mul_f32 v[6:7], v[8:9], v[6:7]
	v_lshl_add_u64 v[10:11], s[88:89], 1, v[138:139]
	v_cvt_pk_f16_f32 v5, v6, v7
	ds_write2_b64 v18, v[2:3], v[4:5] offset0:132 offset1:134
	ds_read_b128 v[2:5], v184
	ds_read_b128 v[6:9], v184 offset:1280
	v_mul_i32_i24_e32 v0, 0x1600, v0
	v_lshl_add_u64 v[12:13], v[10:11], 0, v[0:1]
	v_or_b32_e32 v0, v186, v183
	v_mul_i32_i24_e32 v0, 0x1600, v0
	s_waitcnt lgkmcnt(0)
	global_store_dwordx4 v[12:13], v[2:5], off nt
	s_nop 1
	v_lshl_add_u64 v[2:3], v[10:11], 0, v[0:1]
	global_store_dwordx4 v[2:3], v[6:9], off nt
	ds_read_b128 v[2:5], v184 offset:2560
	ds_read_b128 v[6:9], v184 offset:3840
	v_or_b32_e32 v0, v36, v182
	v_mad_u64_u32 v[12:13], s[20:21], v0, s14, v[10:11]
	v_or_b32_e32 v0, v36, v183
	s_waitcnt lgkmcnt(1)
	global_store_dwordx4 v[12:13], v[2:5], off nt
	s_nop 1
	v_mad_u64_u32 v[2:3], s[20:21], v0, s14, v[10:11]
	s_waitcnt lgkmcnt(0)
	global_store_dwordx4 v[2:3], v[6:9], off nt
	ds_read_b128 v[2:5], v184 offset:5120
	ds_read_b128 v[6:9], v184 offset:6400
	v_or_b32_e32 v0, v37, v182
	v_mad_u64_u32 v[12:13], s[20:21], v0, s14, v[10:11]
	v_or_b32_e32 v0, v37, v183
	s_waitcnt lgkmcnt(1)
	global_store_dwordx4 v[12:13], v[2:5], off nt
	s_nop 1
	v_mad_u64_u32 v[2:3], s[20:21], v0, s14, v[10:11]
	s_waitcnt lgkmcnt(0)
	global_store_dwordx4 v[2:3], v[6:9], off nt
	s_mov_b64 s[20:21], -1
	s_mov_b32 s14, s15
	s_cbranch_vccnz .LBB0_124
